# bccache with full dead-code elimination of the M3 log-decay recomputation (slice-private registers proven dead)
# baseline (speedup 1.0000x reference)
; template <bool PHC>
; __device__ __forceinline__ void gla_pair(const KPD& kp, int l, int pair, unsigned char* lds, int tid, int lane, int wave, v4u& pz0, v4u& pz1, v4u& pw0, v4u& pw1, int next_pair) {
;     ...
;     const int h = item & 3, sc = item >> 2; int b, n, rowbase; chunk_coords(sc, b, n, rowbase);
;     unsigned char* L = lds + half * 69632;
;     const bf16* P = (const bf16*)(kp.ws() + WS_P);
;     float* ST = (float*)(kp.ws() + WS_ST); float* DEC = (float*)(kp.ws() + WS_DEC);
;     const int dir = w4 >> 1, d0 = 24 * (w4 & 1);
;     const bf16* prow = P + (size_t)(rowbase + lane) * INP;
;     v4u vpre[3];
; #pragma unroll
;     for (int i = 0; i < 3; ++i) { const int idx = t4 + 256 * i; vpre[i] = *(const v4u*)(P + (size_t)(rowbase + idx / 12) * INP + C_GV + h * 96 + 8 * (idx % 12)); }
;     v2u spre[9];
;     if constexpr (PHC) { const bf16* SI = (const bf16*)(kp.ws() + WS_SI);
; #pragma unroll
;         for (int i = 0; i < 9; ++i) { const int idx = t4 + 256 * i; const int dd = idx / 1152, e = (idx % 1152) * 4;
;             spre[i] = *(const v2u*)(SI + ((size_t)((dd * 4 + b) * NCH + n) * 4 + h) * 4608 + e); }
;     }
;     float z[16];
;     { const v4u z0 = pz0, z1 = pz1;
;       z[0] = lo16(z0.x); z[1] = hi16(z0.x); z[2] = lo16(z0.y); z[3] = hi16(z0.y); z[4] = lo16(z0.z); z[5] = hi16(z0.z); z[6] = lo16(z0.w); z[7] = hi16(z0.w);
;       z[8] = lo16(z1.x); z[9] = hi16(z1.x); z[10] = lo16(z1.y); z[11] = hi16(z1.y); z[12] = lo16(z1.z); z[13] = hi16(z1.z); z[14] = lo16(z1.w); z[15] = hi16(z1.w); }
;     v4u qraw[3], kraw[3];
; #pragma unroll
;     for (int i = 0; i < 3; ++i) { qraw[i] = *((const v4u*)(prow + C_GQ + h * 48 + d0) + i); kraw[i] = *((const v4u*)(prow + C_GK + h * 48 + d0) + i); }
;     const int wvv[6] = {(int)pw0.x, (int)pw0.y, (int)pw0.z, (int)pw0.w, (int)pw1.x, (int)pw1.y};
;     const int bvv = (int)pw1.z;
;     float bc[24], tot[24];
; #pragma unroll
;     for (int c = 0; c < 24; ++c) {
;         float pre = __int_as_float(__builtin_amdgcn_readlane(bvv, c));
; #pragma unroll
;         for (int r = 0; r < 16; ++r) pre += z[r] * __int_as_float(__builtin_amdgcn_readlane(wvv[(24 * r + c) >> 6], (24 * r + c) & 63));
;         const float la = (fminf(pre, 0.f) - __logf(1.f + __expf(-fabsf(pre)))) * (1.f / 16.f);
;         const float inc = wave_incl_scan(la);
.LBB0_459:
	ds_read_b64 v[250:251], v204
	v_readfirstlane_b32 vcc_lo, v225
	s_lshl_b32 vcc_hi, s2, 2
	s_lshr_b32 vcc_lo, vcc_lo, 6
	s_and_b32 vcc_lo, vcc_lo, 3
	s_add_i32 vcc_lo, vcc_lo, vcc_hi
	s_mul_i32 vcc_lo, vcc_lo, 0x1800
	s_waitcnt lgkmcnt(0)
	v_readfirstlane_b32 s100, v250
	v_readfirstlane_b32 s101, v251
	v_mbcnt_lo_u32_b32 v250, -1, 0
	v_mbcnt_hi_u32_b32 v250, -1, v250
	s_add_u32 s100, s100, 0x3400000
	s_addc_u32 s101, s101, 0
	s_add_u32 s100, s100, vcc_lo
	s_addc_u32 s101, s101, 0
	v_lshlrev_b32_e32 v250, 2, v250
	v_add_u32_e32 v251, 0x1000, v250
	global_load_dword v226, v250, s[100:101]
	global_load_dword v227, v250, s[100:101] offset:256
	global_load_dword v228, v250, s[100:101] offset:512
	global_load_dword v229, v250, s[100:101] offset:768
	global_load_dword v230, v250, s[100:101] offset:1024
	global_load_dword v231, v250, s[100:101] offset:1280
	global_load_dword v232, v250, s[100:101] offset:1536
	global_load_dword v233, v250, s[100:101] offset:1792
	global_load_dword v234, v250, s[100:101] offset:2048
	global_load_dword v235, v250, s[100:101] offset:2304
	global_load_dword v236, v250, s[100:101] offset:2560
	global_load_dword v237, v250, s[100:101] offset:2816
	global_load_dword v238, v250, s[100:101] offset:3072
	global_load_dword v239, v250, s[100:101] offset:3328
	global_load_dword v240, v250, s[100:101] offset:3584
	global_load_dword v241, v250, s[100:101] offset:3840
	global_load_dword v242, v251, s[100:101]
	global_load_dword v243, v251, s[100:101] offset:256
	global_load_dword v244, v251, s[100:101] offset:512
	global_load_dword v245, v251, s[100:101] offset:768
	global_load_dword v246, v251, s[100:101] offset:1024
	global_load_dword v247, v251, s[100:101] offset:1280
	global_load_dword v248, v251, s[100:101] offset:1536
	global_load_dword v249, v251, s[100:101] offset:1792
	v_readlane_b32 s0, v253, 17
	s_add_i32 s3, s0, s3
	v_readlane_b32 s0, v254, 32
	s_add_i32 s59, s59, s0
	v_readlane_b32 s0, v254, 48
	v_readlane_b32 s1, v254, 49
	ds_read_b64 v[2:3], v204
	s_and_b64 s[0:1], s[0:1], exec
	s_cselect_b32 s0, s3, s59
	s_cmp_lt_i32 s0, s87
	s_cselect_b32 s77, s0, -1
	s_lshl_b32 s0, s9, 6
	s_and_b32 s10, s2, 3
	s_add_i32 s80, s8, s0
	s_waitcnt lgkmcnt(0)
	v_readfirstlane_b32 s0, v2
	v_readfirstlane_b32 s1, v3
	s_add_u32 s0, s0, 0x7800000
	s_addc_u32 s1, s1, 0
	ds_read_b64 v[2:3], v204
	s_waitcnt lgkmcnt(0)
	ds_read_b64 v[2:3], v204
	s_mul_i32 s78, s10, 0x60
	s_waitcnt lgkmcnt(0)
	v_add_u32_e32 v2, s80, v37
	v_mov_b64_e32 v[60:61], s[0:1]
	v_add_u32_e32 v4, s80, v82
	v_add_u32_e32 v10, s80, v95
	v_mad_i64_i32 v[2:3], s[0:1], v2, s33, v[60:61]
	s_lshl_b32 s8, s78, 1
	s_mov_b32 s9, s79
	v_mad_i64_i32 v[4:5], s[0:1], v4, s33, v[60:61]
	v_mad_i64_i32 v[10:11], s[0:1], v10, s33, v[60:61]
	v_lshl_add_u64 v[2:3], v[2:3], 0, s[8:9]
	v_lshl_add_u64 v[4:5], v[4:5], 0, s[8:9]
	v_mov_b32_e32 v55, v35
	v_lshl_add_u64 v[10:11], v[10:11], 0, s[8:9]
	v_mov_b32_e32 v57, v35
	v_lshl_add_u64 v[2:3], v[2:3], 0, v[34:35]
	v_lshl_add_u64 v[6:7], v[4:5], 0, v[54:55]
	v_lshl_add_u64 v[10:11], v[10:11], 0, v[56:57]
	global_load_dwordx4 v[2:5], v[2:3], off offset:768
	global_load_dwordx4 v[6:9], v[6:7], off offset:768
	s_mul_i32 s2, s81, 0x84
	global_load_dwordx4 v[10:13], v[10:11], off offset:768
	ds_read_b64 v[14:15], v204
	v_lshlrev_b32_e32 v16, 16, v49
	v_and_b32_e32 v17, 0xffff0000, v49
	v_lshlrev_b32_e32 v18, 16, v42
	v_and_b32_e32 v19, 0xffff0000, v42
	s_waitcnt lgkmcnt(0)
	v_readfirstlane_b32 s0, v14
	v_readfirstlane_b32 s1, v15
	s_add_u32 s0, s0, 0x1a000000
	s_addc_u32 s1, s1, 0
	s_add_i32 s2, s2, s97
	s_ashr_i32 s3, s2, 31
	s_lshl_b64 s[2:3], s[2:3], 2
	s_or_b32 s72, s2, s10
	s_mul_i32 s2, s3, 0x2400
	s_mul_hi_u32 s11, s72, 0x2400
	s_add_i32 s11, s11, s2
	v_lshlrev_b32_e32 v20, 16, v43
	v_and_b32_e32 v21, 0xffff0000, v43
	v_lshlrev_b32_e32 v22, 16, v44
	v_and_b32_e32 v23, 0xffff0000, v44
	v_lshlrev_b32_e32 v24, 16, v45
	v_and_b32_e32 v25, 0xffff0000, v45
	v_lshlrev_b32_e32 v26, 16, v46
	v_and_b32_e32 v27, 0xffff0000, v46
	v_lshlrev_b32_e32 v28, 16, v47
	v_and_b32_e32 v29, 0xffff0000, v47
	v_lshlrev_b32_e32 v30, 16, v48
	v_and_b32_e32 v31, 0xffff0000, v48
	s_mov_b32 s12, 0xbfb8aa3b
	s_mov_b32 s13, 0x800000
	s_mulk_i32 s72, 0x2400
	v_mov_b32_e32 v59, v35
	s_add_u32 s2, s0, s72
	s_addc_u32 s3, s1, s11
	v_mov_b64_e32 v[14:15], s[0:1]
	global_load_dwordx2 v[62:63], v108, s[2:3]
	global_load_dwordx2 v[64:65], v109, s[2:3]
	global_load_dwordx2 v[66:67], v110, s[2:3]
	global_load_dwordx2 v[68:69], v111, s[2:3]
	s_add_u32 s2, s2, 0x1290000
	s_addc_u32 s3, s3, 0
	global_load_dwordx2 v[70:71], v115, s[2:3]
	s_cmp_lt_i32 s77, 0
	v_readlane_b32 s11, v91, 23
	v_readlane_b32 s72, v88, 39
	v_readlane_b32 s73, v88, 63
	v_mov_b32_e32 v38, s11
	v_readlane_b32 s11, v84, 23
	v_pk_mul_f32 v[16:17], v[16:17], s[72:73]
	s_nop 0
	v_fmac_f32_e32 v38, s11, v18
	v_readlane_b32 s11, v84, 47
	s_nop 1
	v_fmac_f32_e32 v38, s11, v19
	v_readlane_b32 s11, v85, 7
	s_nop 1
	v_fmac_f32_e32 v38, s11, v20
	v_readlane_b32 s11, v85, 31
	s_nop 1
	v_fmac_f32_e32 v38, s11, v21
	v_readlane_b32 s11, v85, 55
	s_nop 1
	v_fmac_f32_e32 v38, s11, v22
	v_readlane_b32 s11, v86, 15
	s_nop 1
	v_fmac_f32_e32 v38, s11, v23
	v_readlane_b32 s11, v86, 39
	s_nop 1
	v_fmac_f32_e32 v38, s11, v24
	v_readlane_b32 s11, v86, 63
	s_nop 1
	v_fmac_f32_e32 v38, s11, v25
	v_readlane_b32 s11, v83, 23
	s_nop 1
	v_fmac_f32_e32 v38, s11, v26
	v_readlane_b32 s11, v83, 47
	s_nop 1
	v_fmac_f32_e32 v38, s11, v27
	v_readlane_b32 s11, v87, 7
	s_nop 1
	v_fmac_f32_e32 v38, s11, v28
	v_readlane_b32 s11, v87, 31
	s_nop 1
	v_fmac_f32_e32 v38, s11, v29
	v_readlane_b32 s11, v87, 55
	v_add_u32_e32 v18, s80, v80
	s_nop 0
	v_fmac_f32_e32 v38, s11, v30
	v_readlane_b32 s11, v88, 15
	s_nop 1
	v_fmac_f32_e32 v38, s11, v31
	v_add_f32_e32 v16, v38, v16
	v_add_f32_e32 v38, v16, v17
	v_mul_f32_e64 v16, |v38|, s12
	v_exp_f32_e32 v16, v16
	s_nop 0
	v_add_f32_e32 v16, 1.0, v16
	v_cmp_gt_f32_e32 vcc, s13, v16
	v_add_u32_e32 v16, s81, v89
	s_movk_i32 s0, 0x84
	v_mul_lo_u32 v16, v16, s0
	v_add_u32_e32 v16, s97, v16
	v_ashrrev_i32_e32 v17, 31, v16
	v_lshlrev_b64 v[16:17], 2, v[16:17]
	v_or_b32_e32 v16, s10, v16
	s_movk_i32 s10, 0x2400
	v_mad_u64_u32 v[14:15], s[0:1], v16, s10, v[14:15]
	v_mad_i32_i24 v15, v17, s10, v15
	v_lshl_add_u64 v[14:15], v[14:15], 0, v[58:59]
	global_load_dwordx2 v[72:73], v112, s[2:3]
	global_load_dwordx2 v[74:75], v113, s[2:3]
	global_load_dwordx2 v[76:77], v114, s[2:3]
	global_load_dwordx2 v[78:79], v[14:15], off
	v_mad_i64_i32 v[14:15], s[0:1], v18, s33, v[60:61]
	v_lshl_add_u64 v[14:15], v[14:15], 0, s[78:79]
	s_waitcnt vmcnt(12)
; template <bool PHC>
; __device__ __forceinline__ void gla_pair(const KPD& kp, int l, int pair, unsigned char* lds, int tid, int lane, int wave, v4u& pz0, v4u& pz1, v4u& pw0, v4u& pw1, int next_pair) {
;     ...
;     if constexpr (PHC) { const bf16* SI = (const bf16*)(kp.ws() + WS_SI);
; #pragma unroll
;         for (int i = 0; i < 9; ++i) { const int idx = t4 + 256 * i; const int dd = idx / 1152, e = (idx % 1152) * 4;
;             spre[i] = *(const v2u*)(SI + ((size_t)((dd * 4 + b) * NCH + n) * 4 + h) * 4608 + e); }
;     }
;     float z[16];
;     { const v4u z0 = pz0, z1 = pz1;
;       z[0] = lo16(z0.x); z[1] = hi16(z0.x); z[2] = lo16(z0.y); z[3] = hi16(z0.y); z[4] = lo16(z0.z); z[5] = hi16(z0.z); z[6] = lo16(z0.w); z[7] = hi16(z0.w);
;       z[8] = lo16(z1.x); z[9] = hi16(z1.x); z[10] = lo16(z1.y); z[11] = hi16(z1.y); z[12] = lo16(z1.z); z[13] = hi16(z1.z); z[14] = lo16(z1.w); z[15] = hi16(z1.w); }
;     v4u qraw[3], kraw[3];
; #pragma unroll
;     for (int i = 0; i < 3; ++i) { qraw[i] = *((const v4u*)(prow + C_GQ + h * 48 + d0) + i); kraw[i] = *((const v4u*)(prow + C_GK + h * 48 + d0) + i); }
;     const int wvv[6] = {(int)pw0.x, (int)pw0.y, (int)pw0.z, (int)pw0.w, (int)pw1.x, (int)pw1.y};
;     const int bvv = (int)pw1.z;
;     float bc[24], tot[24];
; #pragma unroll
;     for (int c = 0; c < 24; ++c) {
;         float pre = __int_as_float(__builtin_amdgcn_readlane(bvv, c));
; #pragma unroll
;         for (int r = 0; r < 16; ++r) pre += z[r] * __int_as_float(__builtin_amdgcn_readlane(wvv[(24 * r + c) >> 6], (24 * r + c) & 63));
;         const float la = (fminf(pre, 0.f) - __logf(1.f + __expf(-fabsf(pre)))) * (1.f / 16.f);
;         const float inc = wave_incl_scan(la);
;         const float total = __int_as_float(__builtin_amdgcn_readlane(__float_as_int(inc), 63));
;         bc[c] = dir ? (total - inc + la) : inc; tot[c] = total;
;     }
;     float qv[24], kv[24];
; #pragma unroll
;     for (int i = 0; i < 3; ++i) {
;         qv[8 * i] = lo16(qraw[i].x); qv[8 * i + 1] = hi16(qraw[i].x); qv[8 * i + 2] = lo16(qraw[i].y); qv[8 * i + 3] = hi16(qraw[i].y);
;         qv[8 * i + 4] = lo16(qraw[i].z); qv[8 * i + 5] = hi16(qraw[i].z); qv[8 * i + 6] = lo16(qraw[i].w); qv[8 * i + 7] = hi16(qraw[i].w);
;         kv[8 * i] = lo16(kraw[i].x); kv[8 * i + 1] = hi16(kraw[i].x); kv[8 * i + 2] = lo16(kraw[i].y); kv[8 * i + 3] = hi16(kraw[i].y);
	v_mov_b32_e32 v55, v226
	v_mov_b32_e32 v57, v227
	s_mov_b32 s97, s79
	v_lshl_add_u64 v[30:31], v[14:15], 0, s[96:97]
	global_load_dwordx4 v[26:29], v[30:31], off offset:16
	global_load_dwordx4 v[50:53], v[30:31], off
	global_load_dwordx4 v[14:17], v[30:31], off offset:416
	global_load_dwordx4 v[22:25], v[30:31], off offset:400
	global_load_dwordx4 v[18:21], v[30:31], off offset:32
	global_load_dwordx4 v[30:33], v[30:31], off offset:384
	v_mov_b32_e32 v59, v228
	v_mov_b32_e32 v128, v229
	v_mov_b32_e32 v129, v230
	v_mov_b32_e32 v130, v231
	v_mov_b32_e32 v131, v232
	s_waitcnt vmcnt(0)
	v_lshlrev_b32_e32 v149, 16, v30
	v_and_b32_e32 v30, 0xffff0000, v30
	v_lshlrev_b32_e32 v150, 16, v31
	v_and_b32_e32 v31, 0xffff0000, v31
	v_mov_b32_e32 v132, v233
	v_lshlrev_b32_e32 v152, 16, v33
	v_and_b32_e32 v33, 0xffff0000, v33
	v_lshlrev_b32_e32 v153, 16, v26
	v_and_b32_e32 v26, 0xffff0000, v26
	v_mov_b32_e32 v133, v234
	v_lshlrev_b32_e32 v151, 16, v32
	v_and_b32_e32 v32, 0xffff0000, v32
	v_lshlrev_b32_e32 v155, 16, v28
	v_and_b32_e32 v28, 0xffff0000, v28
	v_mul_f32_e32 v28, 0x3e13cd3a, v28
	v_lshlrev_b32_e32 v156, 16, v29
	v_and_b32_e32 v29, 0xffff0000, v29
	v_mul_f32_e32 v29, 0x3e13cd3a, v29
	v_mov_b32_e32 v134, v235
	v_and_b32_e32 v158, 0xffff0000, v22
	v_lshlrev_b32_e32 v159, 16, v23
	v_lshlrev_b32_e32 v154, 16, v27
	v_and_b32_e32 v27, 0xffff0000, v27
	v_mov_b32_e32 v135, v236
	v_lshlrev_b32_e32 v157, 16, v22
	v_mul_f32_e32 v22, 0x3fb8aa3b, v132
	v_lshlrev_b32_e32 v161, 16, v24
	v_and_b32_e32 v162, 0xffff0000, v24
	v_exp_f32_e32 v22, v22
	v_mul_f32_e32 v24, 0xbfb8aa3b, v132
	v_exp_f32_e32 v24, v24
	v_mov_b32_e32 v136, v237
	v_lshlrev_b32_e32 v165, 16, v18
	v_and_b32_e32 v160, 0xffff0000, v23
	v_mul_f32_e32 v23, 0xbfb8aa3b, v131
	v_exp_f32_e32 v23, v23
	v_and_b32_e32 v164, 0xffff0000, v25
	v_mov_b32_e32 v137, v238
	v_lshlrev_b32_e32 v167, 16, v19
	v_and_b32_e32 v168, 0xffff0000, v19
	v_mul_f32_e32 v19, 0xbfb8aa3b, v59
	v_exp_f32_e32 v19, v19
	v_lshlrev_b32_e32 v163, 16, v25
	v_mul_f32_e32 v25, 0x3fb8aa3b, v135
	v_exp_f32_e32 v25, v25
	v_mov_b32_e32 v138, v239
	v_and_b32_e32 v166, 0xffff0000, v18
	v_and_b32_e32 v170, 0xffff0000, v20
	v_lshlrev_b32_e32 v171, 16, v21
	v_mov_b32_e32 v139, v240
	v_lshlrev_b32_e32 v173, 16, v14
	v_and_b32_e32 v174, 0xffff0000, v14
	v_mul_f32_e32 v14, 0x3fb8aa3b, v55
	v_exp_f32_e32 v14, v14
	v_lshlrev_b32_e32 v169, 16, v20
	v_mul_f32_e32 v20, 0xbfb8aa3b, v128
	v_exp_f32_e32 v20, v20
	v_mov_b32_e32 v140, v241
	v_and_b32_e32 v176, 0xffff0000, v15
	v_lshlrev_b32_e32 v177, 16, v16
	v_and_b32_e32 v172, 0xffff0000, v21
	v_mul_f32_e32 v21, 0x3fb8aa3b, v131
	v_exp_f32_e32 v21, v21
	v_mov_b32_e32 v141, v242
	v_lshlrev_b32_e32 v175, 16, v15
	v_mul_f32_e32 v15, 0x3fb8aa3b, v57
	v_exp_f32_e32 v15, v15
	v_lshlrev_b32_e32 v179, 16, v17
	v_and_b32_e32 v180, 0xffff0000, v17
	v_mul_f32_e32 v17, 0x3fb8aa3b, v59
	v_exp_f32_e32 v17, v17
	v_mov_b32_e32 v142, v243
	v_and_b32_e32 v178, 0xffff0000, v16
	v_mov_b32_e32 v143, v244
	v_mov_b32_e32 v144, v245
	v_mov_b32_e32 v145, v246
	v_mov_b32_e32 v146, v247
	v_lshlrev_b32_e32 v148, 16, v53
	v_and_b32_e32 v53, 0xffff0000, v53
	v_mov_b32_e32 v39, v248
	v_lshlrev_b32_e32 v147, 16, v52
	v_and_b32_e32 v52, 0xffff0000, v52
	v_mov_b32_e32 v38, v249
	v_lshlrev_b32_e32 v40, 16, v50
	v_and_b32_e32 v41, 0xffff0000, v50
	v_mul_f32_e32 v16, 0x3e13cd3a, v40
	v_mul_f32_e32 v14, v16, v14
	v_mul_f32_e32 v16, 0x3e13cd3a, v41
	v_mul_f32_e32 v15, v16, v15
	v_cvt_pk_bf16_f32 v14, v14, v15
	v_mul_f32_e32 v15, 0xbfb8aa3b, v57
	v_mul_f32_e32 v16, 0xbfb8aa3b, v55
	v_exp_f32_e32 v15, v15
	v_exp_f32_e32 v16, v16
	v_lshlrev_b32_e32 v50, 16, v51
	v_and_b32_e32 v51, 0xffff0000, v51
	v_mul_f32_e32 v15, v15, v30
	v_mul_f32_e32 v16, v16, v149
	v_cvt_pk_bf16_f32 v18, v16, v15
	v_mul_f32_e32 v15, 0x3e13cd3a, v50
	v_mul_f32_e32 v15, v15, v17
	v_mul_f32_e32 v17, 0x3fb8aa3b, v128
	v_exp_f32_e32 v17, v17
	v_mul_f32_e32 v16, 0x3e13cd3a, v51
	v_mul_f32_e32 v30, 0xbfb8aa3b, v136
	v_exp_f32_e32 v30, v30
	v_mul_f32_e32 v16, v16, v17
	v_cvt_pk_bf16_f32 v15, v15, v16
	v_mul_f32_e32 v16, v19, v150
	v_mul_f32_e32 v17, v20, v31
	v_cvt_pk_bf16_f32 v19, v16, v17
	v_mul_f32_e32 v16, 0x3fb8aa3b, v129
	v_exp_f32_e32 v16, v16
	v_mul_f32_e32 v17, 0x3fb8aa3b, v130
	v_exp_f32_e32 v17, v17
	v_mul_f32_e32 v20, 0x3e13cd3a, v147
	v_mul_f32_e32 v16, v20, v16
	v_mul_f32_e32 v20, 0x3e13cd3a, v52
	v_mul_f32_e32 v17, v20, v17
	v_mul_f32_e32 v20, 0xbfb8aa3b, v129
	v_cvt_pk_bf16_f32 v16, v16, v17
	v_mul_f32_e32 v17, 0xbfb8aa3b, v130
	v_exp_f32_e32 v20, v20
	v_exp_f32_e32 v17, v17
	v_mul_f32_e32 v31, 0xbfb8aa3b, v139
	v_exp_f32_e32 v31, v31
	v_mul_f32_e32 v20, v20, v151
	v_mul_f32_e32 v17, v17, v32
	v_cvt_pk_bf16_f32 v20, v20, v17
	v_mul_f32_e32 v17, 0x3e13cd3a, v148
	v_mul_f32_e32 v17, v17, v21
	v_mul_f32_e32 v21, 0x3e13cd3a, v53
	v_mul_f32_e32 v21, v21, v22
	v_cvt_pk_bf16_f32 v17, v17, v21
	v_mul_f32_e32 v21, v23, v152
	v_mul_f32_e32 v22, v24, v33
	v_cvt_pk_bf16_f32 v21, v21, v22
	v_mul_f32_e32 v22, 0x3fb8aa3b, v133
	v_exp_f32_e32 v22, v22
	v_mul_f32_e32 v23, 0x3fb8aa3b, v134
	v_exp_f32_e32 v23, v23
	v_mul_f32_e32 v24, 0x3e13cd3a, v153
	v_mul_f32_e32 v22, v24, v22
	v_mul_f32_e32 v24, 0x3e13cd3a, v26
	v_mul_f32_e32 v23, v24, v23
	v_cvt_pk_bf16_f32 v22, v22, v23
	v_mul_f32_e32 v23, 0xbfb8aa3b, v134
	v_mul_f32_e32 v24, 0xbfb8aa3b, v133
	v_exp_f32_e32 v23, v23
	v_exp_f32_e32 v24, v24
	v_mul_f32_e32 v32, 0xbfb8aa3b, v140
	v_exp_f32_e32 v32, v32
	v_mul_f32_e32 v23, v23, v158
	v_mul_f32_e32 v24, v24, v157
	v_cvt_pk_bf16_f32 v26, v24, v23
	v_mul_f32_e32 v23, 0x3e13cd3a, v154
	v_mul_f32_e32 v23, v23, v25
	v_mul_f32_e32 v25, 0x3fb8aa3b, v136
	v_mul_f32_e32 v24, 0x3e13cd3a, v27
; __device__ __forceinline__ unsigned pk2(float lo, float hi) { return cvtpk(lo, hi); }
; template <bool PHC>
; __device__ __forceinline__ void gla_pair(const KPD& kp, int l, int pair, unsigned char* lds, int tid, int lane, int wave, v4u& pz0, v4u& pz1, v4u& pw0, v4u& pw1, int next_pair) {
;     ...
;         const float qs = 0.14433756729740643f;
;         { unsigned qw[12], kw[12];
; #pragma unroll
;           for (int i = 0; i < 12; ++i) { qw[i] = pk2(qv[2 * i] * qs * __expf(bc[2 * i]), qv[2 * i + 1] * qs * __expf(bc[2 * i + 1])); kw[i] = pk2(kv[2 * i] * __expf(-bc[2 * i]), kv[2 * i + 1] * __expf(-bc[2 * i + 1])); }
;           v4u* qo = (v4u*)(AC + lane * 168 + 64 + dir * 48 + d0); v4u* ko = (v4u*)(KI + (dir * 64 + lane) * 56 + d0);
; #pragma unroll
;           for (int i = 0; i < 3; ++i) { qo[i] = (v4u){qw[4 * i], qw[4 * i + 1], qw[4 * i + 2], qw[4 * i + 3]}; ko[i] = (v4u){kw[4 * i], kw[4 * i + 1], kw[4 * i + 2], kw[4 * i + 3]}; } }
; #pragma unroll
;         for (int i = 0; i < 3; ++i) { const int idx = t4 + 256 * i; const int t = idx / 12, ch = idx % 12; *(v4u*)(Vr + t * 104 + 8 * ch) = vpre[i]; }
; #pragma unroll
;         for (int i = 0; i < 9; ++i) { const int idx = t4 + 256 * i; const int dd = idx / 1152, e = (idx % 1152) * 4, d = e / 96, v = e % 96;
;             *(v2u*)(SB + (dd * 48 + d) * 104 + v) = spre[i]; }
;         __syncthreads();
	v_exp_f32_e32 v25, v25
	v_mul_f32_e32 v27, 0xbfb8aa3b, v135
	v_exp_f32_e32 v27, v27
	v_mul_f32_e32 v33, 0x3fb8aa3b, v143
	v_mul_f32_e32 v24, v24, v25
	v_cvt_pk_bf16_f32 v23, v23, v24
	v_mul_f32_e32 v24, v27, v159
	v_mul_f32_e32 v25, v30, v160
	v_cvt_pk_bf16_f32 v27, v24, v25
	v_mul_f32_e32 v24, 0x3fb8aa3b, v137
	v_mul_f32_e32 v25, 0x3fb8aa3b, v138
	v_exp_f32_e32 v24, v24
	v_exp_f32_e32 v25, v25
	v_mul_f32_e32 v30, 0x3e13cd3a, v155
	v_exp_f32_e32 v33, v33
	v_mul_f32_e32 v24, v30, v24
	v_mul_f32_e32 v25, v28, v25
	v_mul_f32_e32 v28, 0xbfb8aa3b, v137
	v_cvt_pk_bf16_f32 v24, v24, v25
	v_mul_f32_e32 v25, 0xbfb8aa3b, v138
	v_exp_f32_e32 v28, v28
	v_exp_f32_e32 v25, v25
	v_mul_f32_e32 v30, 0x3fb8aa3b, v139
	v_exp_f32_e32 v30, v30
	v_mul_f32_e32 v28, v28, v161
	v_mul_f32_e32 v25, v25, v162
	v_cvt_pk_bf16_f32 v28, v28, v25
	v_mul_f32_e32 v25, 0x3e13cd3a, v156
	v_mul_f32_e32 v25, v25, v30
	v_mul_f32_e32 v30, 0x3fb8aa3b, v140
	v_exp_f32_e32 v30, v30
	v_mul_f32_e32 v40, 0xbfb8aa3b, v143
	v_exp_f32_e32 v40, v40
	v_mul_f32_e32 v41, 0xbfb8aa3b, v144
	v_mul_f32_e32 v29, v29, v30
	v_cvt_pk_bf16_f32 v25, v25, v29
	v_mul_f32_e32 v29, v31, v163
	v_mul_f32_e32 v30, v32, v164
	v_cvt_pk_bf16_f32 v29, v29, v30
	v_mul_f32_e32 v30, 0x3fb8aa3b, v141
	v_exp_f32_e32 v30, v30
	v_mul_f32_e32 v31, 0x3fb8aa3b, v142
	v_exp_f32_e32 v31, v31
	v_mul_f32_e32 v32, 0x3e13cd3a, v165
	v_mul_f32_e32 v30, v32, v30
	v_mul_f32_e32 v32, 0x3e13cd3a, v166
	v_mul_f32_e32 v31, v32, v31
	v_cvt_pk_bf16_f32 v30, v30, v31
	v_mul_f32_e32 v31, 0xbfb8aa3b, v142
	v_mul_f32_e32 v32, 0xbfb8aa3b, v141
	v_exp_f32_e32 v31, v31
	v_exp_f32_e32 v32, v32
	v_exp_f32_e32 v41, v41
	v_readlane_b32 s0, v255, 9
	v_mul_f32_e32 v31, v31, v174
	v_mul_f32_e32 v32, v32, v173
	v_cvt_pk_bf16_f32 v50, v32, v31
	v_mul_f32_e32 v31, 0x3e13cd3a, v167
	v_mul_f32_e32 v31, v31, v33
	v_mul_f32_e32 v33, 0x3fb8aa3b, v144
	v_exp_f32_e32 v33, v33
	v_mul_f32_e32 v32, 0x3e13cd3a, v168
	v_readlane_b32 s1, v255, 10
	v_mul_f32_e32 v32, v32, v33
	v_cvt_pk_bf16_f32 v31, v31, v32
	v_mul_f32_e32 v32, v40, v175
	v_mul_f32_e32 v33, v41, v176
	v_cvt_pk_bf16_f32 v51, v32, v33
	v_mul_f32_e32 v32, 0x3fb8aa3b, v145
	v_exp_f32_e32 v32, v32
	v_mul_f32_e32 v33, 0x3fb8aa3b, v146
	v_exp_f32_e32 v33, v33
	v_mul_f32_e32 v40, 0x3e13cd3a, v169
	v_mul_f32_e32 v32, v40, v32
	v_mul_f32_e32 v40, 0x3e13cd3a, v170
	v_mul_f32_e32 v33, v40, v33
	v_cvt_pk_bf16_f32 v32, v32, v33
	v_mul_f32_e32 v33, 0xbfb8aa3b, v146
	v_mul_f32_e32 v40, 0xbfb8aa3b, v145
	v_exp_f32_e32 v33, v33
	v_exp_f32_e32 v40, v40
	v_mul_f32_e32 v41, 0x3fb8aa3b, v39
	v_exp_f32_e32 v41, v41
	v_mul_f32_e32 v33, v33, v178
	v_mul_f32_e32 v40, v40, v177
	v_cvt_pk_bf16_f32 v52, v40, v33
	v_mul_f32_e32 v33, 0x3e13cd3a, v171
	v_mul_f32_e32 v33, v33, v41
	v_mul_f32_e32 v41, 0x3fb8aa3b, v38
	v_mul_f32_e32 v39, 0xbfb8aa3b, v39
	v_mul_f32_e32 v38, 0xbfb8aa3b, v38
	v_exp_f32_e32 v39, v39
	v_exp_f32_e32 v38, v38
	v_exp_f32_e32 v41, v41
	v_mul_f32_e32 v40, 0x3e13cd3a, v172
	v_mul_f32_e32 v39, v39, v179
	v_mul_f32_e32 v38, v38, v180
	v_cvt_pk_bf16_f32 v53, v39, v38
	v_mul_f32_e32 v40, v40, v41
	v_cvt_pk_bf16_f32 v33, v33, v40
	ds_write_b128 v90, v[14:17] offset:128
	ds_write_b128 v92, v[18:21] offset:54784
	ds_write_b128 v90, v[22:25] offset:144
	ds_write_b128 v92, v[26:29] offset:54800
	ds_write_b128 v90, v[30:33] offset:160
	ds_write_b128 v92, v[50:53] offset:54816
	ds_write_b128 v116, v[2:5] offset:21504
	ds_write_b128 v117, v[6:9] offset:21504
	ds_write_b128 v118, v[10:13] offset:21504
	ds_write_b64 v93, v[62:63] offset:34816
	ds_write_b64 v94, v[64:65] offset:34816
	ds_write_b64 v96, v[66:67] offset:34816
	ds_write_b64 v97, v[68:69] offset:34816
	ds_write_b64 v98, v[78:79] offset:34816
	ds_write_b64 v99, v[72:73] offset:44800
	ds_write_b64 v100, v[74:75] offset:44800
	ds_write_b64 v101, v[76:77] offset:44800
	ds_write_b64 v102, v[70:71] offset:44800
	s_waitcnt lgkmcnt(0)
	s_barrier
; __device__ __forceinline__ unsigned cvtpk(float lo, float hi) { unsigned r; asm("v_cvt_pk_bf16_f32 %0, %1, %2" : "=v"(r) : "v"(lo), "v"(hi)); return r; }
; template <bool PHC>
; __device__ __forceinline__ void gla_pair(const KPD& kp, int l, int pair, unsigned char* lds, int tid, int lane, int wave, v4u& pz0, v4u& pz1, v4u& pw0, v4u& pw1, int next_pair) {
;     ...
;         __syncthreads();
;         { const int rt = w4 >> 1, ct = w4 & 1, r32 = lane & 31, hi = lane >> 5;
;           f32x16 af, ab;
; #pragma unroll
;           for (int r = 0; r < 16; ++r) { af[r] = 0.f; ab[r] = 0.f; }
; #pragma unroll
;           for (int ks = 0; ks < 3; ++ks) {
;               const bf16x8 a0 = *(const bf16x8*)(AC + (32 * rt + r32) * 168 + 64 + 16 * ks + 8 * hi);
;               const bf16x8 b0 = *(const bf16x8*)(KI + (32 * ct + r32) * 56 + 16 * ks + 8 * hi);
;               af = __builtin_amdgcn_mfma_f32_32x32x16_bf16(a0, b0, af, 0, 0, 0);
;               const bf16x8 a1 = *(const bf16x8*)(AC + (32 * rt + r32) * 168 + 112 + 16 * ks + 8 * hi);
;               const bf16x8 b1 = *(const bf16x8*)(KI + (64 + 32 * ct + r32) * 56 + 16 * ks + 8 * hi);
;               ab = __builtin_amdgcn_mfma_f32_32x32x16_bf16(a1, b1, ab, 0, 0, 0); }
;           const int j = 32 * ct + r32;
; #pragma unroll
;           for (int r = 0; r < 16; ++r) { const int i = 32 * rt + (r & 3) + 8 * (r >> 2) + 4 * hi;
;               const float val = ((j <= i) ? af[r] : 0.f) + ((j >= i) ? ab[r] : 0.f);
;               AC[i * 168 + j] = (bf16)(cvtpk(val, val) & 0xffffu); } }
;         const int fr = lane & 15, fq = lane >> 4;
;         unsigned short gpre[4][6];
; #pragma unroll
;         for (int r = 0; r < 4; ++r)
; #pragma unroll
;             for (int ct = 0; ct < 6; ++ct) gpre[r][ct] = P[(size_t)(rowbase + 16 * w4 + 4 * fq + r) * INP + C_GG + h * 96 + 16 * ct + fr];
;         __syncthreads();
;         if (next_pair >= 0) gla_prefetch(pz0, pz1, pw0, pw1, kp, l, next_pair, lane, wave);
	ds_read_b128 v[2:5], v103 offset:128
	ds_read_b128 v[6:9], v104 offset:54784
	ds_read_b128 v[50:53], v103 offset:160
	ds_read_b128 v[62:65], v104 offset:54816
	s_waitcnt lgkmcnt(2)
	v_mfma_f32_32x32x16_bf16 v[2:17], v[2:5], v[6:9], 0
	ds_read_b128 v[18:21], v103 offset:224
	ds_read_b128 v[22:25], v104 offset:61952
	ds_read_b128 v[66:69], v103 offset:192
	ds_read_b128 v[70:73], v104 offset:54848
	s_waitcnt lgkmcnt(2)
	v_mfma_f32_32x32x16_bf16 v[18:33], v[18:21], v[22:25], 0
	v_mfma_f32_32x32x16_bf16 v[2:17], v[50:53], v[62:65], v[2:17]
	ds_read_b128 v[50:53], v103 offset:256
	ds_read_b128 v[62:65], v104 offset:61984
	ds_read_b128 v[74:77], v103 offset:288
	ds_read_b128 v[128:131], v104 offset:62016
	s_waitcnt lgkmcnt(2)
	v_mfma_f32_32x32x16_bf16 v[18:33], v[50:53], v[62:65], v[18:33]
	v_add_u32_e32 v64, s80, v105
	v_add_u32_e32 v62, 1, v64
	v_mfma_f32_32x32x16_bf16 v[2:17], v[66:69], v[70:73], v[2:17]
	v_lshlrev_b32_e32 v66, 1, v36
	v_mov_b32_e32 v67, v35
	s_waitcnt lgkmcnt(0)
	v_mfma_f32_32x32x16_bf16 v[18:33], v[74:77], v[128:131], v[18:33]
	s_nop 7
	v_cndmask_b32_e64 v2, v2, 0, s[6:7]
	s_nop 2
	v_cndmask_b32_e64 v18, v18, 0, s[0:1]
	v_mad_i64_i32 v[50:51], s[0:1], v64, s33, v[60:61]
	v_mad_i64_i32 v[52:53], s[0:1], v62, s33, v[60:61]
	v_add_f32_e32 v2, v2, v18
	v_lshl_add_u64 v[50:51], v[50:51], 0, s[8:9]
	v_lshl_add_u64 v[52:53], v[52:53], 0, s[8:9]
	v_cvt_pk_bf16_f32 v2, v2, v2
	ds_write_b16 v119, v2
	v_lshl_add_u64 v[50:51], v[50:51], 0, v[66:67]
	v_lshl_add_u64 v[68:69], v[52:53], 0, v[66:67]
	v_add_u32_e32 v52, 2, v64
	global_load_ushort v136, v[50:51], off offset:1536
	global_load_ushort v135, v[50:51], off offset:1568
	global_load_ushort v134, v[50:51], off offset:1600
	global_load_ushort v133, v[50:51], off offset:1632
	global_load_ushort v131, v[50:51], off offset:1664
	global_load_ushort v129, v[50:51], off offset:1696
	global_load_ushort v128, v[68:69], off offset:1536
	global_load_ushort v79, v[68:69], off offset:1568
	v_mad_i64_i32 v[50:51], s[0:1], v52, s33, v[60:61]
	v_lshl_add_u64 v[50:51], v[50:51], 0, s[8:9]
	v_lshl_add_u64 v[138:139], v[50:51], 0, v[66:67]
	v_add_u32_e32 v50, 3, v64
	v_mad_i64_i32 v[60:61], s[0:1], v50, s33, v[60:61]
	v_lshl_add_u64 v[60:61], v[60:61], 0, s[8:9]
	global_load_ushort v78, v[68:69], off offset:1600
	global_load_ushort v77, v[68:69], off offset:1632
	global_load_ushort v76, v[68:69], off offset:1664
	global_load_ushort v75, v[68:69], off offset:1696
	global_load_ushort v74, v[138:139], off offset:1536
	global_load_ushort v73, v[138:139], off offset:1568
	global_load_ushort v72, v[138:139], off offset:1600
	global_load_ushort v71, v[138:139], off offset:1632
	v_lshl_add_u64 v[140:141], v[60:61], 0, v[66:67]
	global_load_ushort v70, v[138:139], off offset:1664
	global_load_ushort v69, v[138:139], off offset:1696
	global_load_ushort v68, v[140:141], off offset:1536
	global_load_ushort v61, v[140:141], off offset:1568
	global_load_ushort v60, v[140:141], off offset:1600
	global_load_ushort v59, v[140:141], off offset:1632
	global_load_ushort v57, v[140:141], off offset:1664
	global_load_ushort v55, v[140:141], off offset:1696
	v_readlane_b32 s0, v255, 11
	v_readlane_b32 s1, v255, 12
	s_nop 1
	v_cndmask_b32_e64 v2, v3, 0, s[0:1]
	v_cndmask_b32_e64 v3, 0, v19, s[6:7]
	v_add_f32_e32 v2, v2, v3
	v_readlane_b32 s0, v255, 13
	v_cvt_pk_bf16_f32 v2, v2, v2
	v_readlane_b32 s1, v255, 14
	ds_write_b16 v119, v2 offset:336
	s_nop 0
	v_cndmask_b32_e64 v2, v4, 0, s[0:1]
	v_readlane_b32 s0, v255, 15
	v_readlane_b32 s1, v255, 16
	s_nop 1
	v_cndmask_b32_e64 v3, v20, 0, s[0:1]
	v_add_f32_e32 v2, v2, v3
	v_cvt_pk_bf16_f32 v2, v2, v2
	ds_write_b16 v119, v2 offset:672
	v_cndmask_b32_e64 v2, v5, 0, s[16:17]
	v_cndmask_b32_e64 v3, v21, 0, s[18:19]
	v_add_f32_e32 v2, v2, v3
	v_cvt_pk_bf16_f32 v2, v2, v2
	ds_write_b16 v119, v2 offset:1008
	v_cndmask_b32_e64 v2, v6, 0, s[20:21]
	v_cndmask_b32_e64 v3, v22, 0, s[22:23]
	v_add_f32_e32 v2, v2, v3
	v_cvt_pk_bf16_f32 v2, v2, v2
	ds_write_b16 v119, v2 offset:2688
	v_cndmask_b32_e64 v2, v7, 0, s[24:25]
	v_cndmask_b32_e64 v3, v23, 0, s[26:27]
	v_add_f32_e32 v2, v2, v3
	v_cvt_pk_bf16_f32 v2, v2, v2
	ds_write_b16 v119, v2 offset:3024
	v_cndmask_b32_e64 v2, v8, 0, s[28:29]
	v_cndmask_b32_e64 v3, v24, 0, s[30:31]
	v_add_f32_e32 v2, v2, v3
	v_cvt_pk_bf16_f32 v2, v2, v2
	ds_write_b16 v119, v2 offset:3360
	v_cndmask_b32_e64 v2, v9, 0, s[34:35]
	v_cndmask_b32_e64 v3, v25, 0, s[36:37]
	v_add_f32_e32 v2, v2, v3
	v_cvt_pk_bf16_f32 v2, v2, v2
	ds_write_b16 v119, v2 offset:3696
	v_cndmask_b32_e64 v2, v10, 0, s[38:39]
	v_cndmask_b32_e64 v3, v26, 0, s[40:41]
	v_add_f32_e32 v2, v2, v3
	v_cvt_pk_bf16_f32 v2, v2, v2
	ds_write_b16 v119, v2 offset:5376
	v_cndmask_b32_e64 v2, v11, 0, s[42:43]
	v_cndmask_b32_e64 v3, v27, 0, s[44:45]
	v_add_f32_e32 v2, v2, v3
	v_cvt_pk_bf16_f32 v2, v2, v2
	ds_write_b16 v119, v2 offset:5712
	v_cndmask_b32_e64 v2, v12, 0, s[46:47]
	v_cndmask_b32_e64 v3, v28, 0, s[48:49]
	v_add_f32_e32 v2, v2, v3
	v_cvt_pk_bf16_f32 v2, v2, v2
	ds_write_b16 v119, v2 offset:6048
	v_cndmask_b32_e64 v2, v13, 0, s[50:51]
	v_cndmask_b32_e64 v3, v29, 0, s[52:53]
	v_add_f32_e32 v2, v2, v3
	v_cvt_pk_bf16_f32 v2, v2, v2
	ds_write_b16 v119, v2 offset:6384
	v_cndmask_b32_e64 v2, v14, 0, s[54:55]
	v_cndmask_b32_e64 v3, v30, 0, s[56:57]
	v_add_f32_e32 v2, v2, v3
	v_cvt_pk_bf16_f32 v2, v2, v2
	ds_write_b16 v119, v2 offset:8064
	v_cndmask_b32_e64 v2, v15, 0, s[84:85]
	v_cndmask_b32_e64 v3, v31, 0, s[60:61]
	v_add_f32_e32 v2, v2, v3
	v_cvt_pk_bf16_f32 v2, v2, v2
	ds_write_b16 v119, v2 offset:8400
	v_cndmask_b32_e64 v2, v16, 0, s[62:63]
	v_cndmask_b32_e64 v3, v32, 0, s[64:65]
	v_add_f32_e32 v2, v2, v3
	v_cvt_pk_bf16_f32 v2, v2, v2
	ds_write_b16 v119, v2 offset:8736
	v_cndmask_b32_e64 v2, v17, 0, s[66:67]
	v_cndmask_b32_e64 v3, v33, 0, s[68:69]
	v_add_f32_e32 v2, v2, v3
	v_cvt_pk_bf16_f32 v2, v2, v2
	ds_write_b16 v119, v2 offset:9072
	s_waitcnt lgkmcnt(0)
	s_barrier
	s_cbranch_scc1 .LBB0_465
	s_lshl_b32 s2, s77, 1
	s_add_i32 s2, s2, s89
	s_ashr_i32 s9, s2, 2
	s_cmpk_gt_i32 s9, 0x1ff
	s_mov_b64 s[0:1], -1
	s_cbranch_scc0 .LBB0_462
	s_lshl_b32 s0, s9, 6
	s_bfe_u32 s3, s2, 0x20002
	s_and_b32 s8, s0, 0xffffff00
	s_mov_b64 s[0:1], 0
